# v32 + prep maps: every wave gets two q, two k and two v column blocks (was six consecutive blocks: two waves carried all the long k-map epilogues)
# speedup vs baseline: 1.0013x; 1.0013x over previous
; #define LAS __attribute__((address_space(3)))
; #define PARAMS const __attribute__((address_space(4))) Params&
; #define TIDV tid_opaque()
; #define BIDX bid_opaque()
; #define GDIM gdim_opaque()
; DI void prep_phase(PARAMS P, int l, int g, LAS unsigned char* lds, int wave, int lane) {
;     const int tid = TIDV;
;     bf16_t* gb = (bf16_t*)(P.ws + WS_G);
;     const float* SM = (const float*)(P.ws + WS_SM) + (size_t)gbase(g) * 32;
;     const bf16_t* wm = (const bf16_t*)(P.ws + WS_W) + (size_t)l * WL_END + WL_WM;
;     float* DECG = (float*)(P.ws + WS_DECG); float* MCH = (float*)(P.ws + WS_MCH); float* DN = (float*)(P.ws + WS_DN); f32x4* TS = (f32x4*)(P.ws + WS_TS);
;     LAS float* Bl = (LAS float*)(lds + PL_A); LAS bf16_t* Cl = (LAS bf16_t*)(lds + PL_A); LAS bf16_t* Xl = (LAS bf16_t*)(lds + PL_B);
;     LAS float* GAl = (LAS float*)(lds + PL_GA); LAS float* MIl = (LAS float*)(lds + PL_MI); LAS float* MFl = (LAS float*)(lds + PL_MF); LAS float* WSTl = (LAS float*)(lds + PL_WST);
;     const int nch = g == 0 ? 137 : 128;
;     for (int it = BIDX; it < 2 * nch; it += GDIM) {
;         const int cid = it >> 1, part = it & 1;
;         const int row0 = cid * 64, L = (g == 0 && cid == 136) ? 16 : 64;
;         for (int i = tid; i < 64 * 24; i += NTHREADS) { const int t = i / 24, j = i % 24; const float v = SM[(size_t)(row0 + t) * 32 + j];
;             if (j < 4) MIl[t * 4 + j] = v; else if (j < 8) MFl[t * 4 + j - 4] = v; else GAl[t * 16 + j - 8] = v; }
;         __syncthreads();
;         if (part == 0) {
;             const int c = tid & 255, half = tid >> 8, tb = 32 * half; float wa[16];
;     ...
;             const int r = lane & 31, hh = lane >> 5;
; #pragma unroll 1
;             for (int cbk = wave * 6; cbk < wave * 6 + 6; ++cbk) {
;                 const int mt = cbk >> 4, hd = (cbk >> 2) & 3, nb = cbk & 3;
;                 const bf16_t* wt = wm + (size_t)(mt * 4 + hd) * 16384 + (size_t)(32 * nb + r) * 128 + 8 * hh;
.LBB0_690:
	s_andn2_b64 vcc, exec, s[4:5]
	s_cbranch_vccnz .LBB0_755
	s_cmp_eq_u32 s34, 0
	s_cselect_b64 s[8:9], -1, 0
	s_and_b64 s[0:1], s[8:9], exec
	s_movk_i32 s0, 0x112
	s_waitcnt vmcnt(0)
	v_mov_b32_e32 v0, v228
	v_mov_b32_e32 v1, v228
	s_waitcnt vmcnt(0)
	v_mov_b32_e32 v34, v228
	s_mov_b32 s10, s82
	s_cselect_b32 s11, s0, 0x100
	s_cmp_ge_i32 s10, s11
	v_readfirstlane_b32 s2, v1
	s_cbranch_scc1 .LBB0_755
	s_load_dwordx4 s[4:7], s[18:19], 0xe8
	s_load_dwordx4 s[48:51], s[18:19], 0x98
	s_lshl_b32 s0, s34, 13
	s_or_b32 s3, s0, 0x300
	s_mov_b64 s[52:53], s[18:19]
	s_waitcnt lgkmcnt(0)
	s_add_u32 s12, s6, 0x1125a000
	s_addc_u32 s18, s7, 0
	s_and_b64 s[0:1], s[8:9], exec
	s_cselect_b32 s0, 0, s3
	s_ashr_i32 s1, s0, 31
	s_lshl_b64 s[0:1], s[0:1], 7
	s_add_u32 s0, s6, s0
	s_addc_u32 s1, s7, s1
	s_add_u32 s58, s0, 0x10c80000
	s_addc_u32 s59, s1, 0
	s_ashr_i32 s97, s96, 31
	s_mul_i32 s1, s96, 0x2400000
	s_mul_hi_i32 s0, s96, 0x2400000
	s_add_u32 s1, s6, s1
	s_addc_u32 s0, s7, s0
	s_add_u32 s19, s1, 0xe800000
	s_addc_u32 s35, s0, 0
	s_add_u32 s62, s6, 0x111a9000
	s_addc_u32 s63, s7, 0
	s_add_u32 s36, s6, 0x111cb400
	s_addc_u32 s37, s7, 0
	s_add_u32 s0, s6, 0x111cc540
	s_addc_u32 s1, s7, 0
	s_add_u32 s66, s6, 0x1111d000
	s_addc_u32 s67, s7, 0
	s_ashr_i32 s61, s2, 6
	s_load_dwordx8 s[40:47], s[52:53], 0x58
	s_cmp_eq_u32 s61, 4
	s_cselect_b64 s[70:71], -1, 0
	s_lshl_b32 s2, s96, 2
	s_lshl_b64 s[16:17], s[96:97], 14
	s_add_u32 s16, s48, s16
	s_addc_u32 s17, s49, s17
	s_lshl_b64 s[20:21], s[96:97], 13
	s_waitcnt lgkmcnt(0)
	s_add_u32 s20, s44, s20
	s_addc_u32 s21, s45, s21
	s_lshl_b32 s97, s96, 3
	s_lshl_b32 s3, s96, 4
	s_lshl_b32 s33, s34, 2
	s_addk_i32 s97, 0xff80
	s_add_i32 s3, s33, s3
	s_add_u32 s74, s6, 0x1a71a000
	v_writelane_b32 v254, s68, 24
	s_addc_u32 s75, s7, 0
	s_add_u32 s78, s6, 0x1afda000
	v_writelane_b32 v254, s69, 25
	v_writelane_b32 v254, s3, 26
	s_addc_u32 s79, s7, 0
	s_ashr_i32 s3, s2, 31
	s_lshl_b64 s[2:3], s[2:3], 2
	s_add_u32 s82, s40, s2
	s_addc_u32 s83, s41, s3
	v_and_b32_e32 v1, 0xff, v34
	s_add_u32 s86, s42, s2
	s_movk_i32 s2, 0x600
	v_lshl_or_b32 v6, s96, 8, v1
	s_addc_u32 s87, s43, s3
	v_cmp_gt_i32_e64 s[38:39], s2, v34
	v_mov_b32_e32 v4, s50
	v_mov_b32_e32 v5, s51
	s_load_dwordx2 s[2:3], s[52:53], 0x30
	v_ashrrev_i32_e32 v7, 31, v6
	v_lshl_add_u64 v[42:43], v[6:7], 2, v[4:5]
	v_lshl_add_u32 v6, s96, 9, v34
	v_mov_b32_e32 v2, s46
	v_mov_b32_e32 v3, s47
	v_ashrrev_i32_e32 v7, 31, v6
	v_and_b32_e32 v36, 63, v0
	v_ashrrev_i32_e32 v35, 31, v34
	v_lshl_add_u64 v[50:51], v[6:7], 2, v[2:3]
	v_bfe_u32 v6, v0, 5, 1
	v_lshlrev_b64 v[4:5], 2, v[34:35]
	v_lshl_add_u64 v[2:3], v[34:35], 1, s[6:7]
	v_and_b32_e32 v35, 31, v0
	v_lshlrev_b32_e32 v0, 3, v6
	v_lshlrev_b32_e32 v94, 2, v6
	v_lshlrev_b32_e32 v6, 4, v36
	v_lshlrev_b32_e32 v38, 2, v1
	s_waitcnt lgkmcnt(0)
	v_lshl_add_u64 v[54:55], s[2:3], 0, v[4:5]
	v_readlane_b32 s2, v254, 8
	v_readlane_b32 s3, v254, 9
	v_lshlrev_b32_e32 v32, 1, v1
	v_or_b32_e32 v1, 4, v6
	v_add_u32_e32 v97, s2, v1
	v_add_u32_e32 v98, s3, v1
	v_or_b32_e32 v1, 8, v6
	v_mov_b32_e32 v39, v33
	v_add_u32_e32 v99, s2, v1
	v_add_u32_e32 v100, s3, v1
	v_or_b32_e32 v1, 12, v6
	v_lshl_add_u64 v[40:41], s[16:17], 0, v[38:39]
	v_add_u32_e32 v95, s2, v6
	v_add_u32_e32 v96, s3, v6
	v_add_u32_e32 v101, s2, v1
	v_add_u32_e32 v102, s3, v1
	s_mov_b64 s[2:3], 0x1400
	v_lshl_add_u64 v[60:61], v[40:41], 0, s[2:3]
	s_mov_b64 s[2:3], 0x1c00
	v_lshl_add_u64 v[64:65], v[40:41], 0, s[2:3]
	s_mov_b64 s[2:3], 0x2400
	v_lshl_add_u64 v[68:69], v[40:41], 0, s[2:3]
	s_mov_b64 s[2:3], 0x2800
	v_lshl_add_u64 v[70:71], v[40:41], 0, s[2:3]
	s_mov_b64 s[2:3], 0x2c00
	v_lshl_add_u64 v[72:73], v[40:41], 0, s[2:3]
	s_mov_b64 s[2:3], 0x3000
	v_lshl_add_u64 v[74:75], v[40:41], 0, s[2:3]
	s_mov_b64 s[2:3], 0x3400
	v_lshl_add_u64 v[76:77], v[40:41], 0, s[2:3]
	s_mov_b64 s[2:3], 0x3800
	v_lshl_add_u64 v[78:79], v[40:41], 0, s[2:3]
	s_mov_b64 s[2:3], 0x3c00
	v_ashrrev_i32_e32 v8, 3, v34
	v_lshlrev_b32_e32 v10, 2, v34
	v_lshl_add_u64 v[80:81], v[40:41], 0, s[2:3]
	v_readlane_b32 s2, v254, 10
	v_and_b32_e32 v90, 0xffffffe0, v8
	v_lshl_add_u64 v[44:45], s[20:21], 0, v[4:5]
	v_lshl_add_u64 v[56:57], s[4:5], 0, v[4:5]
	v_lshl_add_u64 v[4:5], s[6:7], 0, v[32:33]
	v_add_u32_e32 v119, s2, v10
	s_mov_b64 s[2:3], 0x1913ae00
	v_add_u32_e32 v39, 32, v90
	v_readlane_b32 s17, v254, 7
	s_movk_i32 s16, 0x100
	v_or_b32_e32 v118, 1, v90
	v_lshl_add_u64 v[82:83], v[4:5], 0, s[2:3]
	v_lshlrev_b32_e32 v4, 10, v8
	s_movk_i32 s2, 0x8000
	v_add_u32_e32 v91, s17, v10
	v_cmp_gt_u32_e64 s[42:43], s16, v34
	v_add_u32_e32 v92, s17, v38
	s_mov_b64 s[16:17], 0x130fa000
	v_max_i32_e32 v1, v39, v118
	v_lshlrev_b32_e32 v7, 6, v90
	v_and_or_b32 v4, v4, s2, v38
	s_mov_b64 s[2:3], 0x1959bc00
	v_readlane_b32 s33, v254, 6
	v_add_u32_e32 v9, 0, v38
	s_mov_b64 s[20:21], 0x1800
	v_lshl_add_u64 v[52:53], v[2:3], 0, s[16:17]
	v_and_b32_e32 v6, 1, v1
	v_lshlrev_b32_e32 v11, 10, v90
	v_lshl_add_u64 v[84:85], v[2:3], 0, s[2:3]
	v_add_u32_e32 v2, 0, v7
	s_mov_b64 s[72:73], s[52:53]
	v_lshl_add_u32 v37, v36, 2, s33
	v_cmp_eq_u32_e64 s[40:41], 0, v36
	v_lshl_add_u64 v[46:47], v[44:45], 0, s[84:85]
	v_lshl_add_u64 v[48:49], v[44:45], 0, s[20:21]
	s_lshl_b32 s60, s61, 1
	v_mul_u32_u24_e32 v93, 0x410, v35
	v_cmp_gt_u32_e64 s[44:45], 32, v36
	v_cmp_gt_u32_e64 s[46:47], 2, v36
	v_cmp_gt_u32_e64 s[48:49], 4, v36
	v_cmp_gt_u32_e64 s[50:51], 8, v36
	v_lshl_add_u64 v[58:59], v[40:41], 0, s[84:85]
	v_lshl_add_u64 v[62:63], v[40:41], 0, s[20:21]
	v_lshl_add_u64 v[66:67], v[40:41], 0, s[88:89]
	v_or_b32_e32 v103, 1, v94
	v_or_b32_e32 v104, 2, v94
	v_or_b32_e32 v105, 3, v94
	v_or_b32_e32 v106, 8, v94
	v_or_b32_e32 v107, 9, v94
	v_or_b32_e32 v108, 10, v94
	v_or_b32_e32 v109, 11, v94
	v_or_b32_e32 v110, 16, v94
	v_or_b32_e32 v111, 17, v94
	v_or_b32_e32 v112, 18, v94
	v_or_b32_e32 v113, 19, v94
	v_or_b32_e32 v114, 24, v94
	v_or_b32_e32 v115, 25, v94
	v_or_b32_e32 v116, 26, v94
	v_or_b32_e32 v117, 27, v94
	v_add_u32_e32 v120, 0, v4
	v_lshl_add_u32 v121, v34, 1, s27
	s_mulk_i32 s61, 0xc0
	v_add_u32_e32 v122, 0x20800, v2
	v_add_u32_e32 v123, v9, v11
	v_lshlrev_b32_e32 v86, 1, v0
	v_lshlrev_b32_e32 v124, 2, v36
	v_cmp_gt_u32_e64 s[52:53], 16, v36
	v_cmp_eq_u32_e64 s[54:55], 1, v6
	v_cmp_ne_u32_e64 s[56:57], v1, v118
	s_branch .LBB0_694

; #define LAS __attribute__((address_space(3)))
; #define MFMA32(a, b, c) __builtin_amdgcn_mfma_f32_32x32x16_bf16((a), (b), (c), 0, 0, 0)
; DI void prep_phase(PARAMS P, int l, int g, LAS unsigned char* lds, int wave, int lane) {
;     ...
;             for (int cbk = wave * 6; cbk < wave * 6 + 6; ++cbk) {
;                 const int mt = cbk >> 4, hd = (cbk >> 2) & 3, nb = cbk & 3;
;                 const bf16_t* wt = wm + (size_t)(mt * 4 + hd) * 16384 + (size_t)(32 * nb + r) * 128 + 8 * hh;
;                 const LAS bf16_t* al = (mt == 2 ? Xl : Cl) + r * 520 + hd * 128 + 8 * hh;
;                 f32x16 a0, a1;
; #pragma unroll
;                 for (int i = 0; i < 16; ++i) { a0[i] = 0.f; a1[i] = 0.f; }
; #pragma unroll
;                 for (int ks = 0; ks < 8; ++ks) {
;                     const bf16x8 b = *(const bf16x8*)(wt + 16 * ks);
;                     const bf16x8 x0 = *(const LAS bf16x8*)(al + 16 * ks), x1 = *(const LAS bf16x8*)(al + 32 * 520 + 16 * ks);
;                     a0 = MFMA32(x0, b, a0); a1 = MFMA32(x1, b, a1);
;                 }
;                 const int e = hd * 128 + 32 * nb + r;
.LBB0_746:
	s_lshr_b32 s33, s7, 1
	s_lshl_b32 s33, s33, 4
	s_and_b32 s98, s7, 1
	s_add_i32 s33, s33, s98
	s_add_i32 s33, s33, s60
	s_ashr_i32 s64, s33, 4
	s_bfe_u32 s17, s33, 0x20002
	s_lshl_b32 s4, s64, 2
	s_or_b32 s4, s4, s17
	s_ashr_i32 s5, s4, 31
	s_lshl_b64 s[4:5], s[4:5], 15
	s_add_u32 s4, s19, s4
	s_addc_u32 s5, s35, s5
	s_and_b32 s20, s33, 3
	s_lshl_b32 s20, s20, 5
	v_or_b32_e32 v125, s20, v35
	v_lshlrev_b32_e32 v32, 8, v125
	s_waitcnt lgkmcnt(0)
	v_lshl_add_u64 v[0:1], s[4:5], 0, v[32:33]
	v_mov_b32_e32 v87, v33
	v_lshl_add_u64 v[88:89], v[0:1], 0, v[86:87]
	global_load_dwordx4 v[16:19], v[88:89], off
	global_load_dwordx4 v[130:133], v[88:89], off offset:32
	global_load_dwordx4 v[140:143], v[88:89], off offset:64
	global_load_dwordx4 v[144:147], v[88:89], off offset:96
	global_load_dwordx4 v[148:151], v[88:89], off offset:128
	global_load_dwordx4 v[152:155], v[88:89], off offset:160
	global_load_dwordx4 v[156:159], v[88:89], off offset:192
	global_load_dwordx4 v[160:163], v[88:89], off offset:224
	s_cmp_eq_u32 s64, 2
	s_cselect_b32 s4, s27, 0
	s_lshl_b32 s21, s17, 8
	s_add_i32 s4, s21, s4
	v_add3_u32 v32, s4, v93, v86
	ds_read_b128 v[20:23], v32 offset:33280
	ds_read_b128 v[0:3], v32
	ds_read_b128 v[126:129], v32 offset:32
	ds_read_b128 v[134:137], v32 offset:33312
	s_mov_b64 s[4:5], -1
	s_cmp_lg_u32 s64, 1
	s_waitcnt vmcnt(7) lgkmcnt(2)
	v_mfma_f32_32x32x16_bf16 v[0:15], v[0:3], v[16:19], 0
	s_waitcnt vmcnt(6) lgkmcnt(1)
	v_mfma_f32_32x32x16_bf16 v[0:15], v[126:129], v[130:133], v[0:15]
	v_mfma_f32_32x32x16_bf16 v[16:31], v[20:23], v[16:19], 0
	s_waitcnt lgkmcnt(0)
	v_mfma_f32_32x32x16_bf16 v[16:31], v[134:137], v[130:133], v[16:31]
	ds_read_b128 v[130:133], v32 offset:64
	ds_read_b128 v[134:137], v32 offset:33344
	s_waitcnt vmcnt(5) lgkmcnt(1)
	v_mfma_f32_32x32x16_bf16 v[0:15], v[130:133], v[140:143], v[0:15]
	s_waitcnt lgkmcnt(0)
	v_mfma_f32_32x32x16_bf16 v[16:31], v[134:137], v[140:143], v[16:31]
	ds_read_b128 v[130:133], v32 offset:96
	ds_read_b128 v[134:137], v32 offset:33376
	s_waitcnt vmcnt(4) lgkmcnt(1)
	v_mfma_f32_32x32x16_bf16 v[0:15], v[130:133], v[144:147], v[0:15]
	s_waitcnt lgkmcnt(0)
	v_mfma_f32_32x32x16_bf16 v[16:31], v[134:137], v[144:147], v[16:31]
	ds_read_b128 v[130:133], v32 offset:128
	ds_read_b128 v[134:137], v32 offset:33408
	s_waitcnt vmcnt(3) lgkmcnt(1)
	v_mfma_f32_32x32x16_bf16 v[0:15], v[130:133], v[148:151], v[0:15]
	s_waitcnt lgkmcnt(0)
	v_mfma_f32_32x32x16_bf16 v[16:31], v[134:137], v[148:151], v[16:31]
	ds_read_b128 v[130:133], v32 offset:160
	ds_read_b128 v[134:137], v32 offset:33440
	s_waitcnt vmcnt(2) lgkmcnt(1)
	v_mfma_f32_32x32x16_bf16 v[0:15], v[130:133], v[152:155], v[0:15]
	s_waitcnt lgkmcnt(0)
	v_mfma_f32_32x32x16_bf16 v[16:31], v[134:137], v[152:155], v[16:31]
	ds_read_b128 v[130:133], v32 offset:192
	ds_read_b128 v[134:137], v32 offset:33472
	s_waitcnt vmcnt(1) lgkmcnt(1)
	v_mfma_f32_32x32x16_bf16 v[0:15], v[130:133], v[156:159], v[0:15]
	s_waitcnt lgkmcnt(0)
	v_mfma_f32_32x32x16_bf16 v[16:31], v[134:137], v[156:159], v[16:31]
	ds_read_b128 v[130:133], v32 offset:224
	ds_read_b128 v[134:137], v32 offset:33504
	v_lshl_or_b32 v32, s17, 7, v125
	v_lshlrev_b32_e32 v32, 1, v32
	s_waitcnt vmcnt(0) lgkmcnt(1)
	v_mfma_f32_32x32x16_bf16 v[0:15], v[130:133], v[160:163], v[0:15]
	s_waitcnt lgkmcnt(0)
	v_mfma_f32_32x32x16_bf16 v[16:31], v[134:137], v[160:163], v[16:31]
	s_cbranch_scc1 .LBB0_748
	s_andn2_b64 vcc, exec, s[4:5]
	s_cbranch_vccnz .LBB0_745
	s_branch .LBB0_749
